# nt on the FFN2 A-operand (H) LDS-DMA loads
# baseline (speedup 1.0000x reference)
.LBB0_1997:
	s_add_u32 s2, s10, 0xfff50080
	s_addc_u32 s3, s11, -1
	s_add_i32 s0, 0, 0x10000
	s_cmp_eq_u32 s83, 40
	s_cselect_b32 s3, s73, s3
	s_cselect_b32 s2, s72, s2
	s_cselect_b32 vcc_hi, s77, s55
	s_cselect_b32 vcc_lo, s76, s54
	s_add_i32 s1, 0, 0x14000
	v_add_u32_e32 v140, s0, v234
	v_add_u32_e32 v156, s1, v234
	ds_read_b128 v[128:131], v140
	ds_read_b128 v[132:135], v140 offset:1024
	ds_read_b128 v[136:139], v140 offset:2048
	ds_read_b128 v[140:143], v140 offset:3072
	ds_read_b128 v[144:147], v156
	ds_read_b128 v[148:151], v156 offset:1024
	ds_read_b128 v[152:155], v156 offset:2048
	ds_read_b128 v[156:159], v156 offset:3072
	v_lshl_add_u64 v[212:213], s[10:11], 0, v[202:203]
	s_add_i32 m0, s51, 0xc000
	ds_read_b128 v[160:163], v236
	ds_read_b128 v[164:167], v236 offset:1024
	ds_read_b128 v[168:171], v236 offset:2048
	ds_read_b128 v[172:175], v236 offset:3072
	ds_read_b128 v[176:179], v236 offset:4096
	ds_read_b128 v[180:183], v236 offset:5120
	ds_read_b128 v[204:207], v236 offset:6144
	ds_read_b128 v[208:211], v236 offset:7168
	global_load_lds_dwordx4 v[212:213], off nt
	v_lshl_add_u64 v[212:213], v[212:213], 0, s[62:63]
	s_add_i32 m0, s51, 0xe000
	s_nop 0
	global_load_lds_dwordx4 v[212:213], off nt
	s_waitcnt vmcnt(8)
	s_waitcnt lgkmcnt(0)
	s_barrier
	s_waitcnt lgkmcnt(0)
	v_mfma_f32_16x16x32_bf16 v[124:127], v[128:131], v[160:163], v[124:127]
	v_mfma_f32_16x16x32_bf16 v[120:123], v[136:139], v[160:163], v[120:123]
	v_mfma_f32_16x16x32_bf16 v[108:111], v[128:131], v[168:171], v[108:111]
	v_mfma_f32_16x16x32_bf16 v[104:107], v[136:139], v[168:171], v[104:107]
	v_mfma_f32_16x16x32_bf16 v[92:95], v[128:131], v[176:179], v[92:95]
	v_mfma_f32_16x16x32_bf16 v[88:91], v[136:139], v[176:179], v[88:91]
	v_mfma_f32_16x16x32_bf16 v[76:79], v[128:131], v[204:207], v[76:79]
	v_mfma_f32_16x16x32_bf16 v[72:75], v[136:139], v[204:207], v[72:75]
	v_mfma_f32_16x16x32_bf16 v[124:127], v[132:135], v[164:167], v[124:127]
	v_mfma_f32_16x16x32_bf16 v[120:123], v[140:143], v[164:167], v[120:123]
	v_mfma_f32_16x16x32_bf16 v[108:111], v[132:135], v[172:175], v[108:111]
	v_mfma_f32_16x16x32_bf16 v[104:107], v[140:143], v[172:175], v[104:107]
	v_mfma_f32_16x16x32_bf16 v[92:95], v[132:135], v[180:183], v[92:95]
	v_mfma_f32_16x16x32_bf16 v[88:91], v[140:143], v[180:183], v[88:91]
	v_mfma_f32_16x16x32_bf16 v[76:79], v[132:135], v[208:211], v[76:79]
	v_mfma_f32_16x16x32_bf16 v[72:75], v[140:143], v[208:211], v[72:75]
	v_mfma_f32_16x16x32_bf16 v[116:119], v[144:147], v[160:163], v[116:119]
	v_mfma_f32_16x16x32_bf16 v[112:115], v[152:155], v[160:163], v[112:115]
	v_mfma_f32_16x16x32_bf16 v[100:103], v[144:147], v[168:171], v[100:103]
	v_mfma_f32_16x16x32_bf16 v[96:99], v[152:155], v[168:171], v[96:99]
	v_mfma_f32_16x16x32_bf16 v[84:87], v[144:147], v[176:179], v[84:87]
	v_mfma_f32_16x16x32_bf16 v[80:83], v[152:155], v[176:179], v[80:83]
	v_mfma_f32_16x16x32_bf16 v[68:71], v[144:147], v[204:207], v[68:71]
	v_mfma_f32_16x16x32_bf16 v[64:67], v[152:155], v[204:207], v[64:67]
	v_mfma_f32_16x16x32_bf16 v[116:119], v[148:151], v[164:167], v[116:119]
	v_mfma_f32_16x16x32_bf16 v[112:115], v[156:159], v[164:167], v[112:115]
	v_mfma_f32_16x16x32_bf16 v[100:103], v[148:151], v[172:175], v[100:103]
	v_mfma_f32_16x16x32_bf16 v[96:99], v[156:159], v[172:175], v[96:99]
	v_mfma_f32_16x16x32_bf16 v[84:87], v[148:151], v[180:183], v[84:87]
	v_mfma_f32_16x16x32_bf16 v[80:83], v[156:159], v[180:183], v[80:83]
	v_mfma_f32_16x16x32_bf16 v[68:71], v[148:151], v[208:211], v[68:71]
	v_mfma_f32_16x16x32_bf16 v[64:67], v[156:159], v[208:211], v[64:67]
	s_barrier
	s_add_i32 s0, s0, s50
	v_lshl_add_u64 v[212:213], vcc, 0, v[184:185]
	s_mov_b32 m0, s0
	ds_read_b128 v[160:163], v236 offset:16384
	ds_read_b128 v[164:167], v236 offset:17408
	ds_read_b128 v[168:171], v236 offset:18432
	ds_read_b128 v[172:175], v236 offset:19456
	ds_read_b128 v[176:179], v236 offset:20480
	ds_read_b128 v[180:183], v236 offset:21504
	ds_read_b128 v[204:207], v236 offset:22528
	ds_read_b128 v[208:211], v236 offset:23552
	global_load_lds_dwordx4 v[212:213], off
	v_lshl_add_u64 v[214:215], v[212:213], 0, s[62:63]
	s_add_i32 m0, s0, 0x2000
	s_add_i32 s0, s1, s50
	global_load_lds_dwordx4 v[214:215], off
	v_lshl_add_u64 v[214:215], v[212:213], 0, s[42:43]
	s_mov_b32 m0, s0
	s_nop 0
	global_load_lds_dwordx4 v[214:215], off
	v_lshl_add_u64 v[214:215], v[212:213], 0, s[44:45]
	s_add_i32 m0, s0, 0x2000
	s_nop 0
	global_load_lds_dwordx4 v[214:215], off
	v_lshl_add_u64 v[214:215], s[2:3], 0, v[200:201]
	s_mov_b32 m0, s51
	v_lshl_add_u64 v[216:217], v[214:215], 0, s[62:63]
	global_load_lds_dwordx4 v[214:215], off nt
	s_mov_b32 m0, s66
	s_nop 0
	global_load_lds_dwordx4 v[216:217], off nt
	s_waitcnt vmcnt(8)
	s_waitcnt lgkmcnt(0)
	s_barrier
	s_waitcnt lgkmcnt(0)
	v_mfma_f32_16x16x32_bf16 v[60:63], v[128:131], v[160:163], v[60:63]
	v_mfma_f32_16x16x32_bf16 v[56:59], v[136:139], v[160:163], v[56:59]
	v_mfma_f32_16x16x32_bf16 v[44:47], v[128:131], v[168:171], v[44:47]
	v_mfma_f32_16x16x32_bf16 v[40:43], v[136:139], v[168:171], v[40:43]
	v_mfma_f32_16x16x32_bf16 v[28:31], v[128:131], v[176:179], v[28:31]
	v_mfma_f32_16x16x32_bf16 v[24:27], v[136:139], v[176:179], v[24:27]
	v_mfma_f32_16x16x32_bf16 v[12:15], v[128:131], v[204:207], v[12:15]
	v_mfma_f32_16x16x32_bf16 v[8:11], v[136:139], v[204:207], v[8:11]
	v_mfma_f32_16x16x32_bf16 v[60:63], v[132:135], v[164:167], v[60:63]
	v_mfma_f32_16x16x32_bf16 v[56:59], v[140:143], v[164:167], v[56:59]
	v_mfma_f32_16x16x32_bf16 v[44:47], v[132:135], v[172:175], v[44:47]
	v_mfma_f32_16x16x32_bf16 v[40:43], v[140:143], v[172:175], v[40:43]
	v_mfma_f32_16x16x32_bf16 v[28:31], v[132:135], v[180:183], v[28:31]
	v_mfma_f32_16x16x32_bf16 v[24:27], v[140:143], v[180:183], v[24:27]
	v_mfma_f32_16x16x32_bf16 v[12:15], v[132:135], v[208:211], v[12:15]
	v_mfma_f32_16x16x32_bf16 v[8:11], v[140:143], v[208:211], v[8:11]
	v_mfma_f32_16x16x32_bf16 v[52:55], v[144:147], v[160:163], v[52:55]
	v_mfma_f32_16x16x32_bf16 v[48:51], v[152:155], v[160:163], v[48:51]
	v_mfma_f32_16x16x32_bf16 v[36:39], v[144:147], v[168:171], v[36:39]
	v_mfma_f32_16x16x32_bf16 v[32:35], v[152:155], v[168:171], v[32:35]
	v_mfma_f32_16x16x32_bf16 v[20:23], v[144:147], v[176:179], v[20:23]
	v_mfma_f32_16x16x32_bf16 v[16:19], v[152:155], v[176:179], v[16:19]
	v_mfma_f32_16x16x32_bf16 v[4:7], v[144:147], v[204:207], v[4:7]
	v_mfma_f32_16x16x32_bf16 v[0:3], v[152:155], v[204:207], v[0:3]
	v_mfma_f32_16x16x32_bf16 v[52:55], v[148:151], v[164:167], v[52:55]
	v_mfma_f32_16x16x32_bf16 v[48:51], v[156:159], v[164:167], v[48:51]
	v_mfma_f32_16x16x32_bf16 v[36:39], v[148:151], v[172:175], v[36:39]
	v_mfma_f32_16x16x32_bf16 v[32:35], v[156:159], v[172:175], v[32:35]
	v_mfma_f32_16x16x32_bf16 v[20:23], v[148:151], v[180:183], v[20:23]
	v_mfma_f32_16x16x32_bf16 v[16:19], v[156:159], v[180:183], v[16:19]
	v_mfma_f32_16x16x32_bf16 v[4:7], v[148:151], v[208:211], v[4:7]
	v_mfma_f32_16x16x32_bf16 v[0:3], v[156:159], v[208:211], v[0:3]
	s_barrier
	s_add_i32 s0, 0, 0x18000
	s_add_i32 s1, 0, 0x1c000
	v_add_u32_e32 v140, s0, v234
	v_add_u32_e32 v156, s1, v234
	ds_read_b128 v[128:131], v140
	ds_read_b128 v[132:135], v140 offset:1024
	ds_read_b128 v[136:139], v140 offset:2048
	ds_read_b128 v[140:143], v140 offset:3072
	ds_read_b128 v[144:147], v156
	ds_read_b128 v[148:151], v156 offset:1024
	ds_read_b128 v[152:155], v156 offset:2048
	ds_read_b128 v[156:159], v156 offset:3072
	s_mov_b32 m0, s67
	v_lshl_add_u64 v[216:217], v[214:215], 0, s[42:43]
	ds_read_b128 v[160:163], v236 offset:32768
	ds_read_b128 v[164:167], v236 offset:33792
	ds_read_b128 v[168:171], v236 offset:34816
	ds_read_b128 v[172:175], v236 offset:35840
	ds_read_b128 v[176:179], v236 offset:36864
	ds_read_b128 v[180:183], v236 offset:37888
	ds_read_b128 v[204:207], v236 offset:38912
	ds_read_b128 v[208:211], v236 offset:39936
	global_load_lds_dwordx4 v[216:217], off nt
	v_lshl_add_u64 v[216:217], v[214:215], 0, s[44:45]
	s_mov_b32 m0, s78
	s_nop 0
	global_load_lds_dwordx4 v[216:217], off nt
	s_waitcnt vmcnt(8)
	s_waitcnt lgkmcnt(0)
	s_barrier
	s_waitcnt lgkmcnt(0)
	v_mfma_f32_16x16x32_bf16 v[124:127], v[128:131], v[160:163], v[124:127]
	v_mfma_f32_16x16x32_bf16 v[120:123], v[136:139], v[160:163], v[120:123]
	v_mfma_f32_16x16x32_bf16 v[108:111], v[128:131], v[168:171], v[108:111]
	v_mfma_f32_16x16x32_bf16 v[104:107], v[136:139], v[168:171], v[104:107]
	v_mfma_f32_16x16x32_bf16 v[92:95], v[128:131], v[176:179], v[92:95]
	v_mfma_f32_16x16x32_bf16 v[88:91], v[136:139], v[176:179], v[88:91]
	v_mfma_f32_16x16x32_bf16 v[76:79], v[128:131], v[204:207], v[76:79]
	v_mfma_f32_16x16x32_bf16 v[72:75], v[136:139], v[204:207], v[72:75]
	v_mfma_f32_16x16x32_bf16 v[124:127], v[132:135], v[164:167], v[124:127]
	v_mfma_f32_16x16x32_bf16 v[120:123], v[140:143], v[164:167], v[120:123]
	v_mfma_f32_16x16x32_bf16 v[108:111], v[132:135], v[172:175], v[108:111]
	v_mfma_f32_16x16x32_bf16 v[104:107], v[140:143], v[172:175], v[104:107]
	v_mfma_f32_16x16x32_bf16 v[92:95], v[132:135], v[180:183], v[92:95]
	v_mfma_f32_16x16x32_bf16 v[88:91], v[140:143], v[180:183], v[88:91]
	v_mfma_f32_16x16x32_bf16 v[76:79], v[132:135], v[208:211], v[76:79]
	v_mfma_f32_16x16x32_bf16 v[72:75], v[140:143], v[208:211], v[72:75]
	v_mfma_f32_16x16x32_bf16 v[116:119], v[144:147], v[160:163], v[116:119]
	v_mfma_f32_16x16x32_bf16 v[112:115], v[152:155], v[160:163], v[112:115]
	v_mfma_f32_16x16x32_bf16 v[100:103], v[144:147], v[168:171], v[100:103]
	v_mfma_f32_16x16x32_bf16 v[96:99], v[152:155], v[168:171], v[96:99]
	v_mfma_f32_16x16x32_bf16 v[84:87], v[144:147], v[176:179], v[84:87]
	v_mfma_f32_16x16x32_bf16 v[80:83], v[152:155], v[176:179], v[80:83]
	v_mfma_f32_16x16x32_bf16 v[68:71], v[144:147], v[204:207], v[68:71]
	v_mfma_f32_16x16x32_bf16 v[64:67], v[152:155], v[204:207], v[64:67]
	v_mfma_f32_16x16x32_bf16 v[116:119], v[148:151], v[164:167], v[116:119]
	v_mfma_f32_16x16x32_bf16 v[112:115], v[156:159], v[164:167], v[112:115]
	v_mfma_f32_16x16x32_bf16 v[100:103], v[148:151], v[172:175], v[100:103]
	v_mfma_f32_16x16x32_bf16 v[96:99], v[156:159], v[172:175], v[96:99]
	v_mfma_f32_16x16x32_bf16 v[84:87], v[148:151], v[180:183], v[84:87]
	v_mfma_f32_16x16x32_bf16 v[80:83], v[156:159], v[180:183], v[80:83]
	v_mfma_f32_16x16x32_bf16 v[68:71], v[148:151], v[208:211], v[68:71]
	v_mfma_f32_16x16x32_bf16 v[64:67], v[156:159], v[208:211], v[64:67]
	s_barrier
	s_add_i32 s0, s0, s50
	v_lshl_add_u64 v[216:217], v[212:213], 0, s[90:91]
	s_mov_b32 m0, s0
	ds_read_b128 v[160:163], v236 offset:49152
	ds_read_b128 v[164:167], v236 offset:50176
	ds_read_b128 v[168:171], v236 offset:51200
	ds_read_b128 v[172:175], v236 offset:52224
	ds_read_b128 v[176:179], v236 offset:53248
	ds_read_b128 v[180:183], v236 offset:54272
	ds_read_b128 v[204:207], v236 offset:55296
	ds_read_b128 v[208:211], v236 offset:56320
	global_load_lds_dwordx4 v[216:217], off
	v_lshl_add_u64 v[216:217], v[212:213], 0, s[56:57]
	s_add_i32 m0, s0, 0x2000
	s_add_i32 s0, s1, s50
	global_load_lds_dwordx4 v[216:217], off
	v_lshl_add_u64 v[216:217], v[212:213], 0, s[14:15]
	s_mov_b32 m0, s0
	v_lshl_add_u64 v[212:213], v[212:213], 0, s[52:53]
	global_load_lds_dwordx4 v[216:217], off
	s_add_i32 m0, s0, 0x2000
	s_nop 0
	global_load_lds_dwordx4 v[212:213], off
	v_lshl_add_u64 v[212:213], v[214:215], 0, s[90:91]
	s_mov_b32 m0, s48
	s_nop 0
	global_load_lds_dwordx4 v[212:213], off nt
	v_lshl_add_u64 v[212:213], v[214:215], 0, s[56:57]
	s_mov_b32 m0, s49
	s_nop 0
	global_load_lds_dwordx4 v[212:213], off nt
	s_waitcnt vmcnt(8)
	s_waitcnt lgkmcnt(0)
	s_barrier
	s_waitcnt lgkmcnt(0)
	v_mfma_f32_16x16x32_bf16 v[60:63], v[128:131], v[160:163], v[60:63]
	v_mfma_f32_16x16x32_bf16 v[56:59], v[136:139], v[160:163], v[56:59]
	v_mfma_f32_16x16x32_bf16 v[44:47], v[128:131], v[168:171], v[44:47]
	v_mfma_f32_16x16x32_bf16 v[40:43], v[136:139], v[168:171], v[40:43]
	v_mfma_f32_16x16x32_bf16 v[28:31], v[128:131], v[176:179], v[28:31]
	v_mfma_f32_16x16x32_bf16 v[24:27], v[136:139], v[176:179], v[24:27]
	v_mfma_f32_16x16x32_bf16 v[12:15], v[128:131], v[204:207], v[12:15]
	v_mfma_f32_16x16x32_bf16 v[8:11], v[136:139], v[204:207], v[8:11]
	v_mfma_f32_16x16x32_bf16 v[60:63], v[132:135], v[164:167], v[60:63]
	v_mfma_f32_16x16x32_bf16 v[56:59], v[140:143], v[164:167], v[56:59]
	v_mfma_f32_16x16x32_bf16 v[44:47], v[132:135], v[172:175], v[44:47]
	v_mfma_f32_16x16x32_bf16 v[40:43], v[140:143], v[172:175], v[40:43]
	v_mfma_f32_16x16x32_bf16 v[28:31], v[132:135], v[180:183], v[28:31]
	v_mfma_f32_16x16x32_bf16 v[24:27], v[140:143], v[180:183], v[24:27]
	v_mfma_f32_16x16x32_bf16 v[12:15], v[132:135], v[208:211], v[12:15]
	v_mfma_f32_16x16x32_bf16 v[8:11], v[140:143], v[208:211], v[8:11]
	v_mfma_f32_16x16x32_bf16 v[52:55], v[144:147], v[160:163], v[52:55]
	v_mfma_f32_16x16x32_bf16 v[48:51], v[152:155], v[160:163], v[48:51]
	v_mfma_f32_16x16x32_bf16 v[36:39], v[144:147], v[168:171], v[36:39]
	v_mfma_f32_16x16x32_bf16 v[32:35], v[152:155], v[168:171], v[32:35]
	v_mfma_f32_16x16x32_bf16 v[20:23], v[144:147], v[176:179], v[20:23]
	v_mfma_f32_16x16x32_bf16 v[16:19], v[152:155], v[176:179], v[16:19]
	v_mfma_f32_16x16x32_bf16 v[4:7], v[144:147], v[204:207], v[4:7]
	v_mfma_f32_16x16x32_bf16 v[0:3], v[152:155], v[204:207], v[0:3]
	v_mfma_f32_16x16x32_bf16 v[52:55], v[148:151], v[164:167], v[52:55]
	v_mfma_f32_16x16x32_bf16 v[48:51], v[156:159], v[164:167], v[48:51]
	v_mfma_f32_16x16x32_bf16 v[36:39], v[148:151], v[172:175], v[36:39]
	v_mfma_f32_16x16x32_bf16 v[32:35], v[156:159], v[172:175], v[32:35]
	v_mfma_f32_16x16x32_bf16 v[20:23], v[148:151], v[180:183], v[20:23]
	v_mfma_f32_16x16x32_bf16 v[16:19], v[156:159], v[180:183], v[16:19]
	v_mfma_f32_16x16x32_bf16 v[4:7], v[148:151], v[208:211], v[4:7]
	v_mfma_f32_16x16x32_bf16 v[0:3], v[156:159], v[208:211], v[0:3]
	s_barrier
	s_add_i32 s83, s83, 2
	s_add_u32 s10, s10, 0x100
	s_addc_u32 s11, s11, 0
	s_add_u32 s54, s54, 0x100
	s_addc_u32 s55, s55, 0
	s_cmp_gt_u32 s83, 41
	s_cbranch_scc0 .LBB0_1997
	s_and_b64 vcc, exec, s[36:37]
	s_cbranch_vccz .LBB0_2000
	s_barrier
